# cache-policy: nt removed from the final f32 output stores too
# speedup vs baseline: 1.0003x; 1.0003x over previous
; template <bool FINAL, bool DUMMY = false> __device__ __forceinline__ void norm_rows(const bfu* F, bfu* XB, const float* g1, float* RS, float* xout, int gw, int NGW, int lane, bfu* dummy = nullptr) {
;     ...
;     for (; m < M; m += NGW) {
;         f32x4 f[8], x[8]; float s = 0.f;
; #pragma unroll
;         for (int j = 0; j < 4; ++j) {
;             f[2 * j] = (f32x4){bflo(fw[j].x), bfhi(fw[j].x), bflo(fw[j].y), bfhi(fw[j].y)}; f[2 * j + 1] = (f32x4){bflo(fw[j].z), bfhi(fw[j].z), bflo(fw[j].w), bfhi(fw[j].w)};
;             x[2 * j] = (f32x4){bflo(xw[j].x), bfhi(xw[j].x), bflo(xw[j].y), bfhi(xw[j].y)}; x[2 * j + 1] = (f32x4){bflo(xw[j].z), bfhi(xw[j].z), bflo(xw[j].w), bfhi(xw[j].w)}; }
;         const int mn = m + NGW;
;         if (mn < M) {
; #pragma unroll
;             for (int j = 0; j < 4; ++j) { fw[j] = __builtin_nontemporal_load((const v4u*)(F + (size_t)mn * DM) + lane + 64 * j); xw[j] = ((const v4u*)(XB + (size_t)mn * DM) + lane)[64 * j]; }
;         }
; #pragma unroll
;         for (int k = 0; k < 8; ++k) s += (f[k].x * f[k].x + f[k].y * f[k].y) + (f[k].z * f[k].z + f[k].w * f[k].w);
;         const float rstd1 = 1.f / sqrtf(wave_sum(s) * (1.f / DM) + EPS);
;         float s2 = 0.f;
; #pragma unroll
;         for (int k = 0; k < 8; ++k) { const f32x4 gg = ((const f32x4*)g1)[2 * lane + 128 * (k >> 1) + (k & 1)]; x[k] = x[k] + f[k] * rstd1 * gg; s2 += (x[k].x * x[k].x + x[k].y * x[k].y) + (x[k].z * x[k].z + x[k].w * x[k].w); }
.LBB0_857:
	v_and_b32_e32 v111, 0xffff0000, v64
	v_and_b32_e32 v110, 0xffff0000, v62
	v_and_b32_e32 v115, 0xffff0000, v65
	v_and_b32_e32 v114, 0xffff0000, v63
	v_lshlrev_b32_e32 v109, 16, v64
	v_lshlrev_b32_e32 v108, 16, v62
	v_lshlrev_b32_e32 v113, 16, v65
	v_lshlrev_b32_e32 v112, 16, v63
	v_lshlrev_b32_e32 v84, 16, v34
	v_and_b32_e32 v85, 0xffff0000, v34
	v_lshlrev_b32_e32 v88, 16, v35
	v_and_b32_e32 v89, 0xffff0000, v35
	v_lshlrev_b32_e32 v74, 16, v36
	v_and_b32_e32 v75, 0xffff0000, v36
	v_lshlrev_b32_e32 v80, 16, v37
	v_and_b32_e32 v81, 0xffff0000, v37
	v_pk_mul_f32 v[34:35], v[110:111], v[110:111]
	v_pk_mul_f32 v[36:37], v[114:115], v[114:115]
	v_pk_fma_f32 v[34:35], v[108:109], v[108:109], v[34:35]
	v_pk_fma_f32 v[36:37], v[112:113], v[112:113], v[36:37]
	v_and_b32_e32 v95, 0xffff0000, v55
	v_and_b32_e32 v94, 0xffff0000, v54
	v_pk_add_f32 v[34:35], v[34:35], v[36:37]
	v_lshlrev_b32_e32 v93, 16, v55
	v_lshlrev_b32_e32 v92, 16, v54
	v_lshlrev_b32_e32 v96, 16, v56
	v_and_b32_e32 v97, 0xffff0000, v56
	v_lshlrev_b32_e32 v98, 16, v57
	v_lshlrev_b32_e32 v102, 16, v50
	v_and_b32_e32 v103, 0xffff0000, v50
	v_lshlrev_b32_e32 v50, 16, v46
	v_pk_add_f32 v[34:35], v[34:35], v[34:35] op_sel_hi:[0,1]
	v_pk_mul_f32 v[36:37], v[94:95], v[94:95]
	v_and_b32_e32 v99, 0xffff0000, v57
	v_lshlrev_b32_e32 v106, 16, v51
	v_and_b32_e32 v107, 0xffff0000, v51
	v_lshlrev_b32_e32 v82, 16, v38
	v_and_b32_e32 v83, 0xffff0000, v38
	v_lshlrev_b32_e32 v86, 16, v39
	v_and_b32_e32 v87, 0xffff0000, v39
	v_pk_fma_f32 v[36:37], v[92:93], v[92:93], v[36:37]
	v_mul_f32_e32 v51, v96, v96
	v_mul_f32_e32 v39, v97, v97
	v_mul_f32_e32 v34, v98, v98
	v_mov_b32_e32 v38, v50
	v_lshlrev_b32_e32 v100, 16, v52
	v_and_b32_e32 v101, 0xffff0000, v52
	v_lshlrev_b32_e32 v104, 16, v53
	v_and_b32_e32 v105, 0xffff0000, v53
	v_and_b32_e32 v130, 0xffff0000, v46
	v_lshlrev_b32_e32 v52, 16, v47
	v_and_b32_e32 v53, 0xffff0000, v47
	v_lshlrev_b32_e32 v78, 16, v40
	v_and_b32_e32 v129, 0xffff0000, v40
	v_lshlrev_b32_e32 v76, 16, v41
	v_and_b32_e32 v77, 0xffff0000, v41
	v_pk_add_f32 v[36:37], v[36:37], v[36:37] op_sel_hi:[0,1]
	v_pk_fma_f32 v[40:41], v[98:99], v[98:99], v[34:35] op_sel_hi:[1,1,0]
	v_pk_add_f32 v[38:39], v[50:51], v[38:39]
	v_lshlrev_b32_e32 v62, 16, v42
	v_and_b32_e32 v63, 0xffff0000, v42
	v_lshlrev_b32_e32 v64, 16, v43
	v_and_b32_e32 v65, 0xffff0000, v43
	v_mul_f32_e32 v40, v130, v130
	v_mul_f32_e32 v34, v52, v52
	v_mul_f32_e32 v36, v53, v53
	v_mul_f32_e32 v42, v50, v50
	v_mov_b32_e32 v43, v39
	v_pk_add_f32 v[38:39], v[42:43], v[40:41]
	v_pk_add_f32 v[34:35], v[34:35], v[36:37]
	v_and_b32_e32 v57, 0xffff0000, v49
	v_and_b32_e32 v56, 0xffff0000, v48
	v_pk_add_f32 v[34:35], v[38:39], v[34:35]
	v_lshlrev_b32_e32 v55, 16, v49
	v_lshlrev_b32_e32 v54, 16, v48
	v_pk_add_f32 v[34:35], v[34:35], v[34:35] op_sel_hi:[0,1]
	v_pk_mul_f32 v[36:37], v[56:57], v[56:57]
	v_mul_f32_e32 v79, v82, v82
	v_pk_fma_f32 v[36:37], v[54:55], v[54:55], v[36:37]
	v_mul_f32_e32 v39, v83, v83
	v_mul_f32_e32 v34, v86, v86
	v_mov_b32_e32 v38, v78
	v_pk_add_f32 v[36:37], v[36:37], v[36:37] op_sel_hi:[0,1]
	v_pk_fma_f32 v[40:41], v[86:87], v[86:87], v[34:35] op_sel_hi:[1,1,0]
	v_pk_add_f32 v[38:39], v[78:79], v[38:39]
	v_mul_f32_e32 v40, v129, v129
	v_mul_f32_e32 v36, v76, v76
	v_mul_f32_e32 v34, v77, v77
	v_mul_f32_e32 v42, v78, v78
	v_mov_b32_e32 v43, v39
	v_pk_add_f32 v[38:39], v[42:43], v[40:41]
	v_pk_add_f32 v[34:35], v[36:37], v[34:35]
	v_lshlrev_b32_e32 v118, 16, v58
	v_pk_add_f32 v[34:35], v[38:39], v[34:35]
	v_and_b32_e32 v119, 0xffff0000, v58
	v_add_f32_e32 v34, v34, v35
	v_lshlrev_b32_e32 v122, 16, v59
	v_and_b32_e32 v123, 0xffff0000, v59
	v_lshlrev_b32_e32 v116, 16, v60
	v_and_b32_e32 v117, 0xffff0000, v60
	s_waitcnt lgkmcnt(0)
; template <bool FINAL, bool DUMMY = false> __device__ __forceinline__ void norm_rows(const bfu* F, bfu* XB, const float* g1, float* RS, float* xout, int gw, int NGW, int lane, bfu* dummy = nullptr) {
;     ...
;         for (int k = 0; k < 8; ++k) s += (f[k].x * f[k].x + f[k].y * f[k].y) + (f[k].z * f[k].z + f[k].w * f[k].w);
;         const float rstd1 = 1.f / sqrtf(wave_sum(s) * (1.f / DM) + EPS);
;         float s2 = 0.f;
; #pragma unroll
;         for (int k = 0; k < 8; ++k) { const f32x4 gg = ((const f32x4*)g1)[2 * lane + 128 * (k >> 1) + (k & 1)]; x[k] = x[k] + f[k] * rstd1 * gg; s2 += (x[k].x * x[k].x + x[k].y * x[k].y) + (x[k].z * x[k].z + x[k].w * x[k].w); }
;         if (FINAL) { f32x4* xo = (f32x4*)(xout + (size_t)m * DM);
; #pragma unroll
;             for (int k = 0; k < 8; ++k) __builtin_nontemporal_store(x[k], xo + 2 * lane + 128 * (k >> 1) + (k & 1));
	s_nop 1
	v_add_f32_dpp v34, v34, v34 quad_perm:[1,0,3,2] row_mask:0xf bank_mask:0xf
	v_lshlrev_b32_e32 v120, 16, v61
	v_and_b32_e32 v121, 0xffff0000, v61
	v_lshlrev_b32_e32 v58, 16, v44
	v_and_b32_e32 v59, 0xffff0000, v44
	s_nop 1
	v_add_f32_dpp v34, v34, v34 quad_perm:[2,3,0,1] row_mask:0xf bank_mask:0xf
	v_lshlrev_b32_e32 v60, 16, v45
	v_and_b32_e32 v61, 0xffff0000, v45
	v_mov_b32_e32 v42, v108
	v_mov_b32_e32 v43, v110
	s_nop 1
	v_add_f32_dpp v34, v34, v34 row_half_mirror row_mask:0xf bank_mask:0xf
	v_mov_b32_e32 v44, v112
	v_mov_b32_e32 v45, v114
	v_mov_b32_e32 v110, v109
	v_mov_b32_e32 v114, v113
	s_nop 1
	v_add_f32_dpp v34, v34, v34 row_mirror row_mask:0xf bank_mask:0xf
	v_mov_b32_e32 v109, v94
	v_mov_b32_e32 v94, v93
	v_mov_b32_e32 v108, v92
	v_mov_b32_e32 v51, v130
	v_mov_b32_e32 v35, v34
	s_nop 1
	v_permlane16_swap_b32_e32 v34, v35
	v_add_f32_e32 v34, v34, v35
	v_mov_b32_e32 v79, v129
	s_add_u32 s36, s36, 0x20000
	s_addc_u32 s37, s37, 0
	s_add_u32 s40, s40, 0x20000
	v_mov_b32_e32 v35, v34
	s_nop 1
	v_permlane32_swap_b32_e32 v34, v35
	v_add_f32_e32 v34, v34, v35
	v_fmamk_f32 v34, v34, 0x3a000000, v236
	v_cmp_gt_f32_e32 vcc, s68, v34
	v_mul_f32_e32 v35, 0x4f800000, v34
	s_addc_u32 s41, s41, 0
	v_cndmask_b32_e32 v34, v34, v35, vcc
	v_sqrt_f32_e32 v35, v34
	s_nop 0
	v_add_u32_e32 v36, -1, v35
	v_fma_f32 v37, -v36, v35, v34
	v_cmp_ge_f32_e64 s[38:39], 0, v37
	v_add_u32_e32 v37, 1, v35
	s_nop 0
	v_cndmask_b32_e64 v36, v35, v36, s[38:39]
	v_fma_f32 v35, -v37, v35, v34
	v_cmp_lt_f32_e64 s[38:39], 0, v35
	s_nop 1
	v_cndmask_b32_e64 v35, v36, v37, s[38:39]
	v_mul_f32_e32 v36, 0x37800000, v35
	v_cndmask_b32_e32 v35, v35, v36, vcc
	v_cmp_class_f32_e32 vcc, v34, v234
	s_nop 1
	v_cndmask_b32_e32 v34, v35, v34, vcc
	v_div_scale_f32 v35, s[22:23], v34, v34, 1.0
	v_rcp_f32_e32 v36, v35
	v_readlane_b32 s22, v255, 45
	v_readlane_b32 s23, v255, 46
	v_fma_f32 v37, -v35, v36, 1.0
	v_fmac_f32_e32 v36, v37, v36
	v_div_scale_f32 v37, vcc, 1.0, v34, 1.0
	v_mul_f32_e32 v38, v37, v36
	v_fma_f32 v39, -v35, v38, v37
	v_fmac_f32_e32 v38, v39, v36
	v_fma_f32 v35, -v35, v38, v37
	v_div_fmas_f32 v35, v35, v36, v38
	v_div_fixup_f32 v90, v35, v34, 1.0
	global_load_dwordx4 v[38:41], v[66:67], off offset:16
	global_load_dwordx4 v[34:37], v[66:67], off
	v_pk_mul_f32 v[42:43], v[90:91], v[42:43] op_sel_hi:[0,1]
	v_pk_mul_f32 v[44:45], v[90:91], v[44:45] op_sel_hi:[0,1]
	v_pk_mul_f32 v[92:93], v[90:91], v[94:95] op_sel_hi:[0,1]
	v_pk_mul_f32 v[94:95], v[90:91], v[98:99] op_sel_hi:[0,1]
	v_pk_mul_f32 v[50:51], v[90:91], v[50:51] op_sel_hi:[0,1]
	v_pk_mul_f32 v[52:53], v[90:91], v[52:53] op_sel_hi:[0,1]
	v_pk_mul_f32 v[108:109], v[90:91], v[108:109] op_sel_hi:[0,1]
	v_pk_mul_f32 v[82:83], v[90:91], v[82:83] op_sel_hi:[0,1]
	v_pk_mul_f32 v[86:87], v[90:91], v[86:87] op_sel_hi:[0,1]
	v_pk_mul_f32 v[78:79], v[90:91], v[78:79] op_sel_hi:[0,1]
	v_pk_mul_f32 v[76:77], v[90:91], v[76:77] op_sel_hi:[0,1]
	s_and_b64 vcc, exec, s[42:43]
	s_waitcnt vmcnt(0)
	v_pk_fma_f32 v[36:37], v[36:37], v[44:45], v[122:123]
	v_pk_fma_f32 v[34:35], v[34:35], v[42:43], v[118:119]
	v_pk_mul_f32 v[42:43], v[90:91], v[110:111] op_sel_hi:[0,1]
	v_pk_mul_f32 v[44:45], v[90:91], v[114:115] op_sel_hi:[0,1]
	v_pk_fma_f32 v[40:41], v[40:41], v[44:45], v[120:121]
	v_pk_fma_f32 v[38:39], v[38:39], v[42:43], v[116:117]
	global_load_dwordx4 v[42:45], v[66:67], off offset:2064
	global_load_dwordx4 v[46:49], v[66:67], off offset:2048
	s_waitcnt vmcnt(1)
	v_pk_fma_f32 v[44:45], v[44:45], v[94:95], v[104:105]
	s_waitcnt vmcnt(0)
	v_pk_fma_f32 v[48:49], v[48:49], v[92:93], v[106:107]
	v_pk_mul_f32 v[92:93], v[90:91], v[96:97] op_sel_hi:[0,1]
	v_pk_fma_f32 v[42:43], v[42:43], v[92:93], v[100:101]
	global_load_dwordx4 v[92:95], v[68:69], off offset:16
	global_load_dwordx4 v[96:99], v[68:69], off
	v_pk_fma_f32 v[46:47], v[46:47], v[108:109], v[102:103]
	s_waitcnt vmcnt(0)
	v_pk_fma_f32 v[50:51], v[96:97], v[50:51], v[62:63]
	v_mov_b32_e32 v62, v54
	v_mov_b32_e32 v63, v56
	v_mov_b32_e32 v56, v55
	v_pk_mul_f32 v[62:63], v[90:91], v[62:63] op_sel_hi:[0,1]
	v_pk_mul_f32 v[54:55], v[90:91], v[56:57] op_sel_hi:[0,1]
	v_pk_fma_f32 v[52:53], v[98:99], v[52:53], v[64:65]
	v_pk_fma_f32 v[56:57], v[94:95], v[54:55], v[60:61]
	v_pk_fma_f32 v[54:55], v[92:93], v[62:63], v[58:59]
	global_load_dwordx4 v[58:61], v[70:71], off offset:16
	global_load_dwordx4 v[62:65], v[70:71], off
	s_waitcnt vmcnt(1)
	v_pk_fma_f32 v[60:61], v[60:61], v[76:77], v[80:81]
	s_waitcnt vmcnt(0)
	v_pk_fma_f32 v[64:65], v[64:65], v[86:87], v[88:89]
	v_pk_fma_f32 v[62:63], v[62:63], v[82:83], v[84:85]
	v_pk_fma_f32 v[58:59], v[58:59], v[78:79], v[74:75]
	global_store_dwordx4 v[72:73], v[34:37], off offset:-4096
	global_store_dwordx4 v[72:73], v[38:41], off offset:-4080
	global_store_dwordx4 v[72:73], v[46:49], off offset:-2048
	global_store_dwordx4 v[72:73], v[42:45], off offset:-2032
	global_store_dwordx4 v[72:73], v[50:53], off
	global_store_dwordx4 v[72:73], v[54:57], off offset:16
	global_store_dwordx4 v[72:73], v[62:65], off offset:2048
	global_store_dwordx4 v[72:73], v[58:61], off offset:2064
	v_mov_b64_e32 v[52:53], v[12:13]
	v_mov_b64_e32 v[44:45], v[20:21]
	v_mov_b64_e32 v[60:61], v[4:5]
	v_mov_b64_e32 v[36:37], v[24:25]
	v_mov_b64_e32 v[64:65], v[8:9]
	v_mov_b64_e32 v[56:57], v[16:17]
	v_mov_b64_e32 v[48:49], v[28:29]
	v_mov_b64_e32 v[40:41], v[32:33]
	v_lshl_add_u64 v[72:73], v[72:73], 0, s[22:23]
	v_mov_b64_e32 v[58:59], v[2:3]
	v_mov_b64_e32 v[50:51], v[10:11]
	v_mov_b64_e32 v[42:43], v[18:19]
	v_mov_b64_e32 v[34:35], v[22:23]
	v_mov_b64_e32 v[62:63], v[6:7]
	v_mov_b64_e32 v[54:55], v[14:15]
	v_mov_b64_e32 v[46:47], v[26:27]
	v_mov_b64_e32 v[38:39], v[30:31]
	s_cbranch_vccnz .LBB0_860
